# v13: v7 + phase-1 gate pre-activation dot products re-written by hand (same f32 products as even/odd packed partial sums, 256 packed FMA + 32 adds per row pair, no register shuffles)
# speedup vs baseline: 1.0471x; 1.0072x over previous
; #define LAS __attribute__((address_space(3)))
; __device__ __forceinline__ unsigned cvt_pk_bf16(float lo, float hi) { unsigned r; asm volatile("v_cvt_pk_bf16_f32 %0, %1, %2" : "=v"(r) : "v"(lo), "v"(hi)); return r; }
; __device__ __forceinline__ float dot4(const f32x4 a, const f32x4 b) { return (a[0] * b[0] + a[1] * b[1]) + (a[2] * b[2] + a[3] * b[3]); }
; __device__ __forceinline__ void norm_rows2(const f32x4 (&xa)[4], const f32x4 (&xb)[4], const LAS float* gsa, const LAS float* sha, const LAS float* gsb, const LAS float* shb, const LAS float* WgT, ...
;     float ssa = 0.f, ssb = 0.f;
; #pragma unroll
;     for (int i = 0; i < 4; ++i) { ssa += dot4(xa[i], xa[i]); ssb += dot4(xb[i], xb[i]); }
;     ssa = wave_sum(ssa); ssb = wave_sum(ssb);
;     const float ra = rsqrtf(ssa * (1.0f / 1024.0f) + 1e-6f), rb = rsqrtf(ssb * (1.0f / 1024.0f) + 1e-6f);
;     f32x4 ya[4], yb[4];
; #pragma unroll
;     for (int i = 0; i < 4; ++i) {
;         ya[i] = xa[i] * ra * *(const LAS f32x4*)(gsa + i * 256 + lane * 4) + *(const LAS f32x4*)(sha + i * 256 + lane * 4);
;         yb[i] = xb[i] * rb * *(const LAS f32x4*)(gsb + i * 256 + lane * 4) + *(const LAS f32x4*)(shb + i * 256 + lane * 4);
;         u32x2 w; w.x = cvt_pk_bf16(ya[i][0], ya[i][1]); w.y = cvt_pk_bf16(ya[i][2], ya[i][3]); *(u32x2*)(oa + i * 256 + lane * 4) = w;
;         u32x2 v; v.x = cvt_pk_bf16(yb[i][0], yb[i][1]); v.y = cvt_pk_bf16(yb[i][2], yb[i][3]); *(u32x2*)(ob + i * 256 + lane * 4) = v; }
; __device__ void phase1(const Params& p, LAS unsigned char* lds) {
;     ...
;             const int ra_ = pr < 4 ? rbase + 2 * pr : rbase + 7;
;             const float* xa_ = p.x + (size_t)ra_ * 1024; const float* xb_ = pr < 4 ? xa_ + 1024 : p.ctx + (size_t)crow * 1024;
;             f32x4 xa[4], xb[4];
; #pragma unroll
;             for (int i = 0; i < 4; ++i) { xa[i] = __builtin_nontemporal_load((const f32x4*)(xa_ + i * 256 + lane * 4)); xb[i] = __builtin_nontemporal_load((const f32x4*)(xb_ + i * 256 + lane * 4)); }
;             const LAS float* gsb_ = pr < 4 ? gs : gsc; const LAS float* shb_ = pr < 4 ? sh : shc;
;             bf16_t* ob_ = pr < 4 ? AB + (size_t)(ra_ + 1) * 1024 : AB + (size_t)(16384 + crow) * 1024;
;             float* gb_ = pr < 4 ? gl + ((ra_ + 1) & 2047) : gc;
;             norm_rows2(xa, xb, gs, sh, gsb_, shb_, WgT, AB + (size_t)ra_ * 1024, ob_, gl + (ra_ & 2047), gb_, p.gate_b, lane);
.LBB0_110:
	s_add_i32 s28, 0, 0x2000
	s_add_i32 s29, 0, 0x3000
	s_add_i32 s30, 0, 0x1000
	s_cmp_eq_u32 s82, 8
	v_add_u32_e32 v0, s82, v105
	s_cselect_b64 vcc, -1, 0
	v_cndmask_b32_e32 v60, v0, v108, vcc
	v_ashrrev_i32_e32 v61, 31, v60
	v_lshlrev_b64 v[0:1], 12, v[60:61]
	v_lshl_add_u64 v[0:1], s[36:37], 0, v[0:1]
	v_mov_b32_e32 v49, v35
	s_waitcnt lgkmcnt(0)
	v_lshl_add_u64 v[2:3], v[0:1], 0, v[48:49]
	s_mov_b64 s[38:39], 0x1000
	global_load_dwordx4 v[24:27], v[2:3], off nt
	global_load_dwordx4 v[20:23], v[2:3], off offset:1024 nt
	global_load_dwordx4 v[4:7], v[2:3], off offset:3072 nt
	global_load_dwordx4 v[12:15], v[2:3], off offset:2048 nt
	v_lshl_add_u64 v[0:1], v[0:1], 0, s[38:39]
	v_cndmask_b32_e32 v1, v1, v59, vcc
	v_cndmask_b32_e32 v0, v0, v58, vcc
	v_lshl_add_u64 v[8:9], v[0:1], 0, v[48:49]
	global_load_dwordx4 v[28:31], v[8:9], off nt
	global_load_dwordx4 v[16:19], v[8:9], off offset:1024 nt
	global_load_dwordx4 v[0:3], v[8:9], off offset:3072 nt
	s_nop 0
	global_load_dwordx4 v[8:11], v[8:9], off offset:2048 nt
	s_and_b64 s[38:39], vcc, exec
	s_cselect_b32 s28, s28, 0
	s_cselect_b32 s29, s29, s30
	s_waitcnt vmcnt(7)
	v_pk_mul_f32 v[62:63], v[26:27], v[26:27]
	v_pk_mul_f32 v[64:65], v[24:25], v[24:25]
	s_waitcnt vmcnt(6)
	v_pk_mul_f32 v[66:67], v[22:23], v[22:23]
	v_pk_mul_f32 v[68:69], v[20:21], v[20:21]
	s_waitcnt vmcnt(4)
	v_mul_f32_e32 v70, v15, v15
	v_pk_mov_b32 v[72:73], v[64:65], v[62:63] op_sel:[1,0]
	v_mov_b32_e32 v65, v63
	v_pk_mov_b32 v[62:63], v[68:69], v[66:67] op_sel:[1,0]
	v_mov_b32_e32 v69, v67
	v_mul_f32_e32 v80, v7, v7
	v_mul_f32_e32 v34, v13, v13
	v_pk_fma_f32 v[70:71], v[14:15], v[14:15], v[70:71] op_sel_hi:[1,1,0]
	v_pk_add_f32 v[64:65], v[72:73], v[64:65]
	s_waitcnt vmcnt(3)
	v_pk_mul_f32 v[72:73], v[30:31], v[30:31]
	v_pk_mul_f32 v[74:75], v[28:29], v[28:29]
	v_pk_add_f32 v[62:63], v[62:63], v[68:69]
	s_waitcnt vmcnt(2)
	v_pk_mul_f32 v[68:69], v[18:19], v[18:19]
	v_pk_mul_f32 v[76:77], v[16:17], v[16:17]
	v_mul_f32_e32 v49, v4, v4
	v_mul_f32_e32 v79, v5, v5
	v_mul_f32_e32 v78, v6, v6
	v_pk_fma_f32 v[66:67], v[12:13], v[12:13], v[34:35] op_sel_hi:[1,1,0]
	v_mov_b32_e32 v71, v80
	v_pk_mov_b32 v[80:81], v[74:75], v[72:73] op_sel:[1,0]
	v_mov_b32_e32 v75, v73
	v_pk_mov_b32 v[72:73], v[76:77], v[68:69] op_sel:[1,0]
	v_mov_b32_e32 v77, v69
	v_pk_add_f32 v[64:65], v[64:65], v[64:65] op_sel:[0,1] op_sel_hi:[1,0]
	v_pk_add_f32 v[62:63], v[62:63], v[62:63] op_sel:[0,1] op_sel_hi:[1,0]
	v_mov_b32_e32 v67, v78
	s_waitcnt vmcnt(0)
	v_mul_f32_e32 v34, v9, v9
	v_mul_f32_e32 v78, v11, v11
	v_pk_add_f32 v[74:75], v[80:81], v[74:75]
	v_pk_add_f32 v[72:73], v[72:73], v[76:77]
	v_mov_b32_e32 v65, v49
	v_mov_b32_e32 v63, v79
	v_mul_f32_e32 v82, v0, v0
	v_mul_f32_e32 v83, v1, v1
	v_mul_f32_e32 v84, v2, v2
	v_mul_f32_e32 v85, v3, v3
	v_pk_add_f32 v[66:67], v[66:67], v[70:71]
	v_pk_fma_f32 v[68:69], v[8:9], v[8:9], v[34:35] op_sel_hi:[1,1,0]
	v_pk_fma_f32 v[70:71], v[10:11], v[10:11], v[78:79] op_sel_hi:[1,1,0]
	v_pk_add_f32 v[62:63], v[64:65], v[62:63]
	v_pk_add_f32 v[64:65], v[74:75], v[74:75] op_sel:[0,1] op_sel_hi:[1,0]
	v_pk_add_f32 v[72:73], v[72:73], v[72:73] op_sel:[0,1] op_sel_hi:[1,0]
	v_mov_b32_e32 v69, v84
	v_mov_b32_e32 v71, v85
	v_mov_b32_e32 v65, v82
	v_mov_b32_e32 v73, v83
	v_pk_add_f32 v[68:69], v[68:69], v[70:71]
	v_pk_add_f32 v[64:65], v[64:65], v[72:73]
	v_pk_add_f32 v[62:63], v[62:63], v[66:67]
	v_pk_add_f32 v[64:65], v[64:65], v[68:69]
	v_mov_b32_e32 v67, v62
	v_mov_b32_e32 v66, v64
	v_mov_b32_e32 v62, v65
	v_pk_add_f32 v[62:63], v[66:67], v[62:63]
	ds_bpermute_b32 v65, v53, v63
	ds_bpermute_b32 v64, v53, v62
	v_lshlrev_b64 v[76:77], 11, v[60:61]
	v_add_u32_e32 v49, s28, v48
	v_add_u32_e32 v61, s29, v48
	v_add_u32_e32 v34, 1, v60
	s_waitcnt lgkmcnt(0)
	v_pk_add_f32 v[62:63], v[62:63], v[64:65]
	ds_bpermute_b32 v65, v94, v63
	ds_bpermute_b32 v64, v94, v62
	v_cndmask_b32_e32 v74, v34, v109, vcc
	v_ashrrev_i32_e32 v75, 31, v74
	v_lshlrev_b64 v[74:75], 11, v[74:75]
	v_lshl_add_u64 v[78:79], v[36:37], 0, v[76:77]
	s_waitcnt lgkmcnt(0)
	v_pk_add_f32 v[62:63], v[62:63], v[64:65]
	ds_bpermute_b32 v73, v95, v63
	ds_bpermute_b32 v72, v95, v62
	ds_read_b128 v[64:67], v99
	ds_read_b128 v[68:71], v99 offset:4096
	ds_read_b128 v[80:83], v49
	ds_read_b128 v[84:87], v61
	s_waitcnt lgkmcnt(4)
	v_pk_add_f32 v[62:63], v[62:63], v[72:73]
	ds_bpermute_b32 v73, v96, v63
	ds_bpermute_b32 v72, v96, v62
	s_waitcnt lgkmcnt(0)
	v_pk_add_f32 v[62:63], v[62:63], v[72:73]
	ds_bpermute_b32 v73, v97, v63
	ds_bpermute_b32 v72, v97, v62
	s_waitcnt lgkmcnt(0)
	v_pk_add_f32 v[62:63], v[62:63], v[72:73]
	ds_bpermute_b32 v73, v98, v63
	ds_bpermute_b32 v72, v98, v62
	s_waitcnt lgkmcnt(0)
	v_pk_add_f32 v[62:63], v[62:63], v[72:73]
	s_nop 0
	v_pk_fma_f32 v[62:63], v[62:63], s[46:47], v[50:51] op_sel_hi:[1,0,0]
	s_nop 0
	v_mul_f32_e32 v72, 0x4b800000, v63
	v_cmp_gt_f32_e64 s[28:29], s34, v63
	v_mul_f32_e32 v73, 0x4b800000, v62
	v_cmp_gt_f32_e64 s[30:31], s34, v62
	v_cndmask_b32_e64 v63, v63, v72, s[28:29]
	v_rsq_f32_e32 v72, v63
	v_cndmask_b32_e64 v62, v62, v73, s[30:31]
	v_rsq_f32_e32 v73, v62
	v_lshl_add_u64 v[62:63], v[36:37], 0, v[74:75]
	v_mul_f32_e32 v74, 0x45800000, v72
	v_cndmask_b32_e64 v88, v72, v74, s[28:29]
	v_mul_f32_e32 v75, 0x45800000, v73
	v_cndmask_b32_e64 v90, v73, v75, s[30:31]
	v_pk_mul_f32 v[24:25], v[24:25], v[88:89] op_sel_hi:[1,0]
	v_pk_mul_f32 v[26:27], v[26:27], v[88:89] op_sel_hi:[1,0]
	v_pk_mul_f32 v[28:29], v[28:29], v[90:91] op_sel_hi:[1,0]
	v_pk_mul_f32 v[30:31], v[30:31], v[90:91] op_sel_hi:[1,0]
	v_pk_mul_f32 v[92:93], v[20:21], v[88:89] op_sel_hi:[1,0]
	v_pk_fma_f32 v[74:75], v[66:67], v[26:27], v[70:71]
	v_pk_fma_f32 v[76:77], v[64:65], v[24:25], v[68:69]
	v_pk_mul_f32 v[110:111], v[22:23], v[88:89] op_sel_hi:[1,0]
	v_cvt_pk_bf16_f32 v20, v76, v77
	v_cvt_pk_bf16_f32 v21, v74, v75
	v_pk_fma_f32 v[70:71], v[82:83], v[30:31], v[86:87]
	v_pk_fma_f32 v[72:73], v[80:81], v[28:29], v[84:85]
	global_store_dwordx2 v[78:79], v[20:21], off
	v_cvt_pk_bf16_f32 v64, v72, v73
	v_cvt_pk_bf16_f32 v65, v70, v71
	ds_read_b128 v[20:23], v99 offset:1024
	ds_read_b128 v[24:27], v99 offset:5120
	ds_read_b128 v[28:31], v49 offset:1024
	ds_read_b128 v[80:83], v61 offset:1024
	v_pk_mul_f32 v[16:17], v[16:17], v[90:91] op_sel_hi:[1,0]
	global_store_dwordx2 v[62:63], v[64:65], off
	v_pk_mul_f32 v[18:19], v[18:19], v[90:91] op_sel_hi:[1,0]
	s_waitcnt lgkmcnt(2)
; #define LAS __attribute__((address_space(3)))
; __device__ __forceinline__ unsigned cvt_pk_bf16(float lo, float hi) { unsigned r; asm volatile("v_cvt_pk_bf16_f32 %0, %1, %2" : "=v"(r) : "v"(lo), "v"(hi)); return r; }
; __device__ __forceinline__ float dot4(const f32x4 a, const f32x4 b) { return (a[0] * b[0] + a[1] * b[1]) + (a[2] * b[2] + a[3] * b[3]); }
; __device__ __forceinline__ void norm_rows2(const f32x4 (&xa)[4], const f32x4 (&xb)[4], const LAS float* gsa, const LAS float* sha, const LAS float* gsb, const LAS float* shb, const LAS float* WgT, ...
;     ...
;     for (int i = 0; i < 4; ++i) {
;         ya[i] = xa[i] * ra * *(const LAS f32x4*)(gsa + i * 256 + lane * 4) + *(const LAS f32x4*)(sha + i * 256 + lane * 4);
;         yb[i] = xb[i] * rb * *(const LAS f32x4*)(gsb + i * 256 + lane * 4) + *(const LAS f32x4*)(shb + i * 256 + lane * 4);
;         u32x2 w; w.x = cvt_pk_bf16(ya[i][0], ya[i][1]); w.y = cvt_pk_bf16(ya[i][2], ya[i][3]); *(u32x2*)(oa + i * 256 + lane * 4) = w;
;         u32x2 v; v.x = cvt_pk_bf16(yb[i][0], yb[i][1]); v.y = cvt_pk_bf16(yb[i][2], yb[i][3]); *(u32x2*)(ob + i * 256 + lane * 4) = v; }
;     f32x4 pa[4], pb[4];
; #pragma unroll
;     for (int jq = 0; jq < 4; ++jq) { f32x4 sa = (f32x4){0.f, 0.f, 0.f, 0.f}, sb = sa;
; #pragma unroll
;         for (int i = 0; i < 4; ++i) { const LAS float* wp = WgT + (jq * 4) * 1024 + i * 256 + lane * 4;
;             const f32x4 w0 = *(const LAS f32x4*)wp, w1 = *(const LAS f32x4*)(wp + 1024), w2 = *(const LAS f32x4*)(wp + 2048), w3 = *(const LAS f32x4*)(wp + 3072);
;             sa += (f32x4){dot4(ya[i], w0), dot4(ya[i], w1), dot4(ya[i], w2), dot4(ya[i], w3)};
;             sb += (f32x4){dot4(yb[i], w0), dot4(yb[i], w1), dot4(yb[i], w2), dot4(yb[i], w3)}; }
	v_pk_fma_f32 v[66:67], v[110:111], v[22:23], v[26:27]
	v_pk_fma_f32 v[68:69], v[92:93], v[20:21], v[24:25]
	s_waitcnt lgkmcnt(0)
	v_pk_fma_f32 v[64:65], v[16:17], v[28:29], v[80:81]
	v_cvt_pk_bf16_f32 v16, v68, v69
	v_cvt_pk_bf16_f32 v17, v66, v67
	v_pk_fma_f32 v[30:31], v[18:19], v[30:31], v[82:83]
	global_store_dwordx2 v[78:79], v[16:17], off offset:512
	v_cvt_pk_bf16_f32 v16, v64, v65
	v_cvt_pk_bf16_f32 v17, v30, v31
	global_store_dwordx2 v[62:63], v[16:17], off offset:512
	ds_read_b128 v[16:19], v99 offset:2048
	ds_read_b128 v[20:23], v99 offset:6144
	ds_read_b128 v[24:27], v49 offset:2048
	ds_read_b128 v[80:83], v61 offset:2048
	v_pk_mul_f32 v[12:13], v[12:13], v[88:89] op_sel_hi:[1,0]
	v_pk_mul_f32 v[14:15], v[14:15], v[88:89] op_sel_hi:[1,0]
	v_pk_mul_f32 v[8:9], v[8:9], v[90:91] op_sel_hi:[1,0]
	s_waitcnt lgkmcnt(2)
	v_pk_fma_f32 v[14:15], v[14:15], v[18:19], v[22:23]
	v_pk_fma_f32 v[18:19], v[12:13], v[16:17], v[20:21]
	v_pk_mul_f32 v[10:11], v[10:11], v[90:91] op_sel_hi:[1,0]
	s_waitcnt lgkmcnt(0)
	v_pk_fma_f32 v[20:21], v[8:9], v[24:25], v[80:81]
	v_cvt_pk_bf16_f32 v8, v18, v19
	v_cvt_pk_bf16_f32 v9, v14, v15
	v_pk_fma_f32 v[16:17], v[10:11], v[26:27], v[82:83]
	global_store_dwordx2 v[78:79], v[8:9], off offset:1024
	v_cvt_pk_bf16_f32 v8, v20, v21
	v_cvt_pk_bf16_f32 v9, v16, v17
	global_store_dwordx2 v[62:63], v[8:9], off offset:1024
	ds_read_b128 v[8:11], v99 offset:3072
	ds_read_b128 v[22:25], v99 offset:7168
	v_pk_mul_f32 v[12:13], v[4:5], v[88:89] op_sel_hi:[1,0]
	v_pk_mul_f32 v[80:81], v[6:7], v[88:89] op_sel_hi:[1,0]
	ds_read_b128 v[4:7], v49 offset:3072
	ds_read_b128 v[26:29], v61 offset:3072
	v_pk_mul_f32 v[0:1], v[0:1], v[90:91] op_sel_hi:[1,0]
	s_waitcnt lgkmcnt(2)
	v_pk_fma_f32 v[10:11], v[80:81], v[10:11], v[24:25]
	v_pk_fma_f32 v[12:13], v[12:13], v[8:9], v[22:23]
	v_pk_mul_f32 v[2:3], v[2:3], v[90:91] op_sel_hi:[1,0]
	s_waitcnt lgkmcnt(0)
	v_pk_fma_f32 v[8:9], v[0:1], v[4:5], v[26:27]
	v_cvt_pk_bf16_f32 v0, v12, v13
	v_cvt_pk_bf16_f32 v1, v10, v11
	v_pk_fma_f32 v[6:7], v[2:3], v[6:7], v[28:29]
	global_store_dwordx2 v[78:79], v[0:1], off offset:1536
	v_cvt_pk_bf16_f32 v4, v8, v9
	v_cvt_pk_bf16_f32 v5, v6, v7
	global_store_dwordx2 v[62:63], v[4:5], off offset:1536
	ds_read_b128 v[110:113], v99 offset:16384
	ds_read_b128 v[114:117], v99 offset:20480
	ds_read_b128 v[118:121], v99 offset:24576
	ds_read_b128 v[122:125], v99 offset:28672
	ds_read_b128 v[126:129], v99 offset:32768
	ds_read_b128 v[130:133], v99 offset:36864
	ds_read_b128 v[134:137], v99 offset:40960
	ds_read_b128 v[138:141], v99 offset:45056
	ds_read_b128 v[142:145], v99 offset:49152
	ds_read_b128 v[146:149], v99 offset:53248
	ds_read_b128 v[150:153], v99 offset:57344
	ds_read_b128 v[154:157], v99 offset:61440
	s_waitcnt lgkmcnt(8)
	v_pk_mul_f32 v[160:161], v[72:73], v[110:111]
	v_pk_mul_f32 v[192:193], v[76:77], v[110:111]
	v_pk_mul_f32 v[162:163], v[72:73], v[114:115]
	v_pk_mul_f32 v[194:195], v[76:77], v[114:115]
	v_pk_mul_f32 v[164:165], v[72:73], v[118:119]
	v_pk_mul_f32 v[196:197], v[76:77], v[118:119]
	v_pk_mul_f32 v[166:167], v[72:73], v[122:123]
	v_pk_mul_f32 v[198:199], v[76:77], v[122:123]
	v_pk_fma_f32 v[160:161], v[70:71], v[112:113], v[160:161]
	v_pk_fma_f32 v[192:193], v[74:75], v[112:113], v[192:193]
	v_pk_fma_f32 v[162:163], v[70:71], v[116:117], v[162:163]
	v_pk_fma_f32 v[194:195], v[74:75], v[116:117], v[194:195]
	v_pk_fma_f32 v[164:165], v[70:71], v[120:121], v[164:165]
	v_pk_fma_f32 v[196:197], v[74:75], v[120:121], v[196:197]
	v_pk_fma_f32 v[166:167], v[70:71], v[124:125], v[166:167]
	v_pk_fma_f32 v[198:199], v[74:75], v[124:125], v[198:199]
	ds_read_b128 v[228:231], v100 offset:49152
	ds_read_b128 v[232:235], v100 offset:53248
	ds_read_b128 v[236:239], v100 offset:57344
	ds_read_b128 v[240:243], v100 offset:61440
	s_waitcnt lgkmcnt(8)
	v_pk_mul_f32 v[168:169], v[72:73], v[126:127]
	v_pk_mul_f32 v[200:201], v[76:77], v[126:127]
	v_pk_mul_f32 v[170:171], v[72:73], v[130:131]
	v_pk_mul_f32 v[202:203], v[76:77], v[130:131]
	v_pk_mul_f32 v[172:173], v[72:73], v[134:135]
	v_pk_mul_f32 v[204:205], v[76:77], v[134:135]
	v_pk_mul_f32 v[174:175], v[72:73], v[138:139]
	v_pk_mul_f32 v[206:207], v[76:77], v[138:139]
	v_pk_fma_f32 v[168:169], v[70:71], v[128:129], v[168:169]
	v_pk_fma_f32 v[200:201], v[74:75], v[128:129], v[200:201]
	v_pk_fma_f32 v[170:171], v[70:71], v[132:133], v[170:171]
	v_pk_fma_f32 v[202:203], v[74:75], v[132:133], v[202:203]
	v_pk_fma_f32 v[172:173], v[70:71], v[136:137], v[172:173]
	v_pk_fma_f32 v[204:205], v[74:75], v[136:137], v[204:205]
	v_pk_fma_f32 v[174:175], v[70:71], v[140:141], v[174:175]
	v_pk_fma_f32 v[206:207], v[74:75], v[140:141], v[206:207]
	ds_read_b128 v[110:113], v99 offset:17408
	ds_read_b128 v[114:117], v99 offset:21504
	ds_read_b128 v[118:121], v99 offset:25600
	ds_read_b128 v[122:125], v99 offset:29696
	s_waitcnt lgkmcnt(8)
	v_pk_mul_f32 v[176:177], v[72:73], v[142:143]
	v_pk_mul_f32 v[208:209], v[76:77], v[142:143]
	v_pk_mul_f32 v[178:179], v[72:73], v[146:147]
	v_pk_mul_f32 v[210:211], v[76:77], v[146:147]
	v_pk_mul_f32 v[180:181], v[72:73], v[150:151]
	v_pk_mul_f32 v[212:213], v[76:77], v[150:151]
	v_pk_mul_f32 v[182:183], v[72:73], v[154:155]
	v_pk_mul_f32 v[214:215], v[76:77], v[154:155]
	v_pk_fma_f32 v[176:177], v[70:71], v[144:145], v[176:177]
	v_pk_fma_f32 v[208:209], v[74:75], v[144:145], v[208:209]
	v_pk_fma_f32 v[178:179], v[70:71], v[148:149], v[178:179]
	v_pk_fma_f32 v[210:211], v[74:75], v[148:149], v[210:211]
	v_pk_fma_f32 v[180:181], v[70:71], v[152:153], v[180:181]
	v_pk_fma_f32 v[212:213], v[74:75], v[152:153], v[212:213]
	v_pk_fma_f32 v[182:183], v[70:71], v[156:157], v[182:183]
	v_pk_fma_f32 v[214:215], v[74:75], v[156:157], v[214:215]
	ds_read_b128 v[126:129], v99 offset:33792
	ds_read_b128 v[130:133], v99 offset:37888
	ds_read_b128 v[134:137], v99 offset:41984
	ds_read_b128 v[138:141], v99 offset:46080
	s_waitcnt lgkmcnt(8)
; #define LAS __attribute__((address_space(3)))
; __device__ __forceinline__ float dot4(const f32x4 a, const f32x4 b) { return (a[0] * b[0] + a[1] * b[1]) + (a[2] * b[2] + a[3] * b[3]); }
; __device__ __forceinline__ void norm_rows2(const f32x4 (&xa)[4], const f32x4 (&xb)[4], const LAS float* gsa, const LAS float* sha, const LAS float* gsb, const LAS float* shb, const LAS float* WgT, ...
;     ...
;     for (int jq = 0; jq < 4; ++jq) { f32x4 sa = (f32x4){0.f, 0.f, 0.f, 0.f}, sb = sa;
; #pragma unroll
;         for (int i = 0; i < 4; ++i) { const LAS float* wp = WgT + (jq * 4) * 1024 + i * 256 + lane * 4;
;             const f32x4 w0 = *(const LAS f32x4*)wp, w1 = *(const LAS f32x4*)(wp + 1024), w2 = *(const LAS f32x4*)(wp + 2048), w3 = *(const LAS f32x4*)(wp + 3072);
;             sa += (f32x4){dot4(ya[i], w0), dot4(ya[i], w1), dot4(ya[i], w2), dot4(ya[i], w3)};
;             sb += (f32x4){dot4(yb[i], w0), dot4(yb[i], w1), dot4(yb[i], w2), dot4(yb[i], w3)}; }
;         pa[jq] = sa; pb[jq] = sb; }
	v_pk_mul_f32 v[184:185], v[72:73], v[228:229]
	v_pk_mul_f32 v[216:217], v[76:77], v[228:229]
	v_pk_mul_f32 v[186:187], v[72:73], v[232:233]
	v_pk_mul_f32 v[218:219], v[76:77], v[232:233]
	v_pk_mul_f32 v[188:189], v[72:73], v[236:237]
	v_pk_mul_f32 v[220:221], v[76:77], v[236:237]
	v_pk_mul_f32 v[190:191], v[72:73], v[240:241]
	v_pk_mul_f32 v[222:223], v[76:77], v[240:241]
	v_pk_fma_f32 v[184:185], v[70:71], v[230:231], v[184:185]
	v_pk_fma_f32 v[216:217], v[74:75], v[230:231], v[216:217]
	v_pk_fma_f32 v[186:187], v[70:71], v[234:235], v[186:187]
	v_pk_fma_f32 v[218:219], v[74:75], v[234:235], v[218:219]
	v_pk_fma_f32 v[188:189], v[70:71], v[238:239], v[188:189]
	v_pk_fma_f32 v[220:221], v[74:75], v[238:239], v[220:221]
	v_pk_fma_f32 v[190:191], v[70:71], v[242:243], v[190:191]
	v_pk_fma_f32 v[222:223], v[74:75], v[242:243], v[222:223]
	ds_read_b128 v[142:145], v99 offset:50176
	ds_read_b128 v[146:149], v99 offset:54272
	ds_read_b128 v[150:153], v99 offset:58368
	ds_read_b128 v[154:157], v99 offset:62464
	s_waitcnt lgkmcnt(8)
	v_pk_fma_f32 v[160:161], v[64:65], v[110:111], v[160:161]
	v_pk_fma_f32 v[192:193], v[68:69], v[110:111], v[192:193]
	v_pk_fma_f32 v[162:163], v[64:65], v[114:115], v[162:163]
	v_pk_fma_f32 v[194:195], v[68:69], v[114:115], v[194:195]
	v_pk_fma_f32 v[164:165], v[64:65], v[118:119], v[164:165]
	v_pk_fma_f32 v[196:197], v[68:69], v[118:119], v[196:197]
	v_pk_fma_f32 v[166:167], v[64:65], v[122:123], v[166:167]
	v_pk_fma_f32 v[198:199], v[68:69], v[122:123], v[198:199]
	v_pk_fma_f32 v[160:161], v[30:31], v[112:113], v[160:161]
	v_pk_fma_f32 v[192:193], v[66:67], v[112:113], v[192:193]
	v_pk_fma_f32 v[162:163], v[30:31], v[116:117], v[162:163]
	v_pk_fma_f32 v[194:195], v[66:67], v[116:117], v[194:195]
	v_pk_fma_f32 v[164:165], v[30:31], v[120:121], v[164:165]
	v_pk_fma_f32 v[196:197], v[66:67], v[120:121], v[196:197]
	v_pk_fma_f32 v[166:167], v[30:31], v[124:125], v[166:167]
	v_pk_fma_f32 v[198:199], v[66:67], v[124:125], v[198:199]
	ds_read_b128 v[228:231], v100 offset:50176
	ds_read_b128 v[232:235], v100 offset:54272
	ds_read_b128 v[236:239], v100 offset:58368
	ds_read_b128 v[240:243], v100 offset:62464
	s_waitcnt lgkmcnt(8)
	v_pk_fma_f32 v[168:169], v[64:65], v[126:127], v[168:169]
	v_pk_fma_f32 v[200:201], v[68:69], v[126:127], v[200:201]
	v_pk_fma_f32 v[170:171], v[64:65], v[130:131], v[170:171]
	v_pk_fma_f32 v[202:203], v[68:69], v[130:131], v[202:203]
	v_pk_fma_f32 v[172:173], v[64:65], v[134:135], v[172:173]
	v_pk_fma_f32 v[204:205], v[68:69], v[134:135], v[204:205]
	v_pk_fma_f32 v[174:175], v[64:65], v[138:139], v[174:175]
	v_pk_fma_f32 v[206:207], v[68:69], v[138:139], v[206:207]
	v_pk_fma_f32 v[168:169], v[30:31], v[128:129], v[168:169]
	v_pk_fma_f32 v[200:201], v[66:67], v[128:129], v[200:201]
	v_pk_fma_f32 v[170:171], v[30:31], v[132:133], v[170:171]
	v_pk_fma_f32 v[202:203], v[66:67], v[132:133], v[202:203]
	v_pk_fma_f32 v[172:173], v[30:31], v[136:137], v[172:173]
	v_pk_fma_f32 v[204:205], v[66:67], v[136:137], v[204:205]
	v_pk_fma_f32 v[174:175], v[30:31], v[140:141], v[174:175]
	v_pk_fma_f32 v[206:207], v[66:67], v[140:141], v[206:207]
	ds_read_b128 v[110:113], v99 offset:18432
	ds_read_b128 v[114:117], v99 offset:22528
	ds_read_b128 v[118:121], v99 offset:26624
	ds_read_b128 v[122:125], v99 offset:30720
	s_waitcnt lgkmcnt(8)
	v_pk_fma_f32 v[176:177], v[64:65], v[142:143], v[176:177]
	v_pk_fma_f32 v[208:209], v[68:69], v[142:143], v[208:209]
	v_pk_fma_f32 v[178:179], v[64:65], v[146:147], v[178:179]
	v_pk_fma_f32 v[210:211], v[68:69], v[146:147], v[210:211]
	v_pk_fma_f32 v[180:181], v[64:65], v[150:151], v[180:181]
	v_pk_fma_f32 v[212:213], v[68:69], v[150:151], v[212:213]
	v_pk_fma_f32 v[182:183], v[64:65], v[154:155], v[182:183]
	v_pk_fma_f32 v[214:215], v[68:69], v[154:155], v[214:215]
	v_pk_fma_f32 v[176:177], v[30:31], v[144:145], v[176:177]
	v_pk_fma_f32 v[208:209], v[66:67], v[144:145], v[208:209]
	v_pk_fma_f32 v[178:179], v[30:31], v[148:149], v[178:179]
	v_pk_fma_f32 v[210:211], v[66:67], v[148:149], v[210:211]
	v_pk_fma_f32 v[180:181], v[30:31], v[152:153], v[180:181]
	v_pk_fma_f32 v[212:213], v[66:67], v[152:153], v[212:213]
	v_pk_fma_f32 v[182:183], v[30:31], v[156:157], v[182:183]
	v_pk_fma_f32 v[214:215], v[66:67], v[156:157], v[214:215]
	ds_read_b128 v[126:129], v99 offset:34816
	ds_read_b128 v[130:133], v99 offset:38912
	ds_read_b128 v[134:137], v99 offset:43008
	ds_read_b128 v[138:141], v99 offset:47104
	s_waitcnt lgkmcnt(8)
	v_pk_fma_f32 v[184:185], v[64:65], v[228:229], v[184:185]
	v_pk_fma_f32 v[216:217], v[68:69], v[228:229], v[216:217]
	v_pk_fma_f32 v[186:187], v[64:65], v[232:233], v[186:187]
	v_pk_fma_f32 v[218:219], v[68:69], v[232:233], v[218:219]
	v_pk_fma_f32 v[188:189], v[64:65], v[236:237], v[188:189]
	v_pk_fma_f32 v[220:221], v[68:69], v[236:237], v[220:221]
	v_pk_fma_f32 v[190:191], v[64:65], v[240:241], v[190:191]
	v_pk_fma_f32 v[222:223], v[68:69], v[240:241], v[222:223]
	v_pk_fma_f32 v[184:185], v[30:31], v[230:231], v[184:185]
	v_pk_fma_f32 v[216:217], v[66:67], v[230:231], v[216:217]
	v_pk_fma_f32 v[186:187], v[30:31], v[234:235], v[186:187]
	v_pk_fma_f32 v[218:219], v[66:67], v[234:235], v[218:219]
	v_pk_fma_f32 v[188:189], v[30:31], v[238:239], v[188:189]
	v_pk_fma_f32 v[220:221], v[66:67], v[238:239], v[220:221]
	v_pk_fma_f32 v[190:191], v[30:31], v[242:243], v[190:191]
	v_pk_fma_f32 v[222:223], v[66:67], v[242:243], v[222:223]
	ds_read_b128 v[142:145], v99 offset:51200
	ds_read_b128 v[146:149], v99 offset:55296
	ds_read_b128 v[150:153], v99 offset:59392
	ds_read_b128 v[154:157], v99 offset:63488
	s_waitcnt lgkmcnt(8)
; #define LAS __attribute__((address_space(3)))
; __device__ __forceinline__ float dot4(const f32x4 a, const f32x4 b) { return (a[0] * b[0] + a[1] * b[1]) + (a[2] * b[2] + a[3] * b[3]); }
; __device__ __forceinline__ void norm_rows2(const f32x4 (&xa)[4], const f32x4 (&xb)[4], const LAS float* gsa, const LAS float* sha, const LAS float* gsb, const LAS float* shb, const LAS float* WgT, ...
;     ...
;     for (int jq = 0; jq < 4; ++jq) { f32x4 sa = (f32x4){0.f, 0.f, 0.f, 0.f}, sb = sa;
; #pragma unroll
;         for (int i = 0; i < 4; ++i) { const LAS float* wp = WgT + (jq * 4) * 1024 + i * 256 + lane * 4;
;             const f32x4 w0 = *(const LAS f32x4*)wp, w1 = *(const LAS f32x4*)(wp + 1024), w2 = *(const LAS f32x4*)(wp + 2048), w3 = *(const LAS f32x4*)(wp + 3072);
;             sa += (f32x4){dot4(ya[i], w0), dot4(ya[i], w1), dot4(ya[i], w2), dot4(ya[i], w3)};
;             sb += (f32x4){dot4(yb[i], w0), dot4(yb[i], w1), dot4(yb[i], w2), dot4(yb[i], w3)}; }
;         pa[jq] = sa; pb[jq] = sb; }
	v_pk_fma_f32 v[160:161], v[20:21], v[110:111], v[160:161]
	v_pk_fma_f32 v[192:193], v[18:19], v[110:111], v[192:193]
	v_pk_fma_f32 v[162:163], v[20:21], v[114:115], v[162:163]
	v_pk_fma_f32 v[194:195], v[18:19], v[114:115], v[194:195]
	v_pk_fma_f32 v[164:165], v[20:21], v[118:119], v[164:165]
	v_pk_fma_f32 v[196:197], v[18:19], v[118:119], v[196:197]
	v_pk_fma_f32 v[166:167], v[20:21], v[122:123], v[166:167]
	v_pk_fma_f32 v[198:199], v[18:19], v[122:123], v[198:199]
	v_pk_fma_f32 v[160:161], v[16:17], v[112:113], v[160:161]
	v_pk_fma_f32 v[192:193], v[14:15], v[112:113], v[192:193]
	v_pk_fma_f32 v[162:163], v[16:17], v[116:117], v[162:163]
	v_pk_fma_f32 v[194:195], v[14:15], v[116:117], v[194:195]
	v_pk_fma_f32 v[164:165], v[16:17], v[120:121], v[164:165]
	v_pk_fma_f32 v[196:197], v[14:15], v[120:121], v[196:197]
	v_pk_fma_f32 v[166:167], v[16:17], v[124:125], v[166:167]
	v_pk_fma_f32 v[198:199], v[14:15], v[124:125], v[198:199]
	ds_read_b128 v[228:231], v100 offset:51200
	ds_read_b128 v[232:235], v100 offset:55296
	ds_read_b128 v[236:239], v100 offset:59392
	ds_read_b128 v[240:243], v100 offset:63488
	s_waitcnt lgkmcnt(8)
	v_pk_fma_f32 v[168:169], v[20:21], v[126:127], v[168:169]
	v_pk_fma_f32 v[200:201], v[18:19], v[126:127], v[200:201]
	v_pk_fma_f32 v[170:171], v[20:21], v[130:131], v[170:171]
	v_pk_fma_f32 v[202:203], v[18:19], v[130:131], v[202:203]
	v_pk_fma_f32 v[172:173], v[20:21], v[134:135], v[172:173]
	v_pk_fma_f32 v[204:205], v[18:19], v[134:135], v[204:205]
	v_pk_fma_f32 v[174:175], v[20:21], v[138:139], v[174:175]
	v_pk_fma_f32 v[206:207], v[18:19], v[138:139], v[206:207]
	v_pk_fma_f32 v[168:169], v[16:17], v[128:129], v[168:169]
	v_pk_fma_f32 v[200:201], v[14:15], v[128:129], v[200:201]
	v_pk_fma_f32 v[170:171], v[16:17], v[132:133], v[170:171]
	v_pk_fma_f32 v[202:203], v[14:15], v[132:133], v[202:203]
	v_pk_fma_f32 v[172:173], v[16:17], v[136:137], v[172:173]
	v_pk_fma_f32 v[204:205], v[14:15], v[136:137], v[204:205]
	v_pk_fma_f32 v[174:175], v[16:17], v[140:141], v[174:175]
	v_pk_fma_f32 v[206:207], v[14:15], v[140:141], v[206:207]
	ds_read_b128 v[110:113], v99 offset:19456
	ds_read_b128 v[114:117], v99 offset:23552
	ds_read_b128 v[118:121], v99 offset:27648
	ds_read_b128 v[122:125], v99 offset:31744
	s_waitcnt lgkmcnt(8)
	v_pk_fma_f32 v[176:177], v[20:21], v[142:143], v[176:177]
	v_pk_fma_f32 v[208:209], v[18:19], v[142:143], v[208:209]
	v_pk_fma_f32 v[178:179], v[20:21], v[146:147], v[178:179]
	v_pk_fma_f32 v[210:211], v[18:19], v[146:147], v[210:211]
	v_pk_fma_f32 v[180:181], v[20:21], v[150:151], v[180:181]
	v_pk_fma_f32 v[212:213], v[18:19], v[150:151], v[212:213]
	v_pk_fma_f32 v[182:183], v[20:21], v[154:155], v[182:183]
	v_pk_fma_f32 v[214:215], v[18:19], v[154:155], v[214:215]
	v_pk_fma_f32 v[176:177], v[16:17], v[144:145], v[176:177]
	v_pk_fma_f32 v[208:209], v[14:15], v[144:145], v[208:209]
	v_pk_fma_f32 v[178:179], v[16:17], v[148:149], v[178:179]
	v_pk_fma_f32 v[210:211], v[14:15], v[148:149], v[210:211]
	v_pk_fma_f32 v[180:181], v[16:17], v[152:153], v[180:181]
	v_pk_fma_f32 v[212:213], v[14:15], v[152:153], v[212:213]
	v_pk_fma_f32 v[182:183], v[16:17], v[156:157], v[182:183]
	v_pk_fma_f32 v[214:215], v[14:15], v[156:157], v[214:215]
	ds_read_b128 v[126:129], v99 offset:35840
	ds_read_b128 v[130:133], v99 offset:39936
	ds_read_b128 v[134:137], v99 offset:44032
	ds_read_b128 v[138:141], v99 offset:48128
	s_waitcnt lgkmcnt(8)
	v_pk_fma_f32 v[184:185], v[20:21], v[228:229], v[184:185]
	v_pk_fma_f32 v[216:217], v[18:19], v[228:229], v[216:217]
	v_pk_fma_f32 v[186:187], v[20:21], v[232:233], v[186:187]
	v_pk_fma_f32 v[218:219], v[18:19], v[232:233], v[218:219]
	v_pk_fma_f32 v[188:189], v[20:21], v[236:237], v[188:189]
	v_pk_fma_f32 v[220:221], v[18:19], v[236:237], v[220:221]
	v_pk_fma_f32 v[190:191], v[20:21], v[240:241], v[190:191]
	v_pk_fma_f32 v[222:223], v[18:19], v[240:241], v[222:223]
	v_pk_fma_f32 v[184:185], v[16:17], v[230:231], v[184:185]
	v_pk_fma_f32 v[216:217], v[14:15], v[230:231], v[216:217]
	v_pk_fma_f32 v[186:187], v[16:17], v[234:235], v[186:187]
	v_pk_fma_f32 v[218:219], v[14:15], v[234:235], v[218:219]
	v_pk_fma_f32 v[188:189], v[16:17], v[238:239], v[188:189]
	v_pk_fma_f32 v[220:221], v[14:15], v[238:239], v[220:221]
	v_pk_fma_f32 v[190:191], v[16:17], v[242:243], v[190:191]
	v_pk_fma_f32 v[222:223], v[14:15], v[242:243], v[222:223]
	ds_read_b128 v[142:145], v99 offset:52224
	ds_read_b128 v[146:149], v99 offset:56320
	ds_read_b128 v[150:153], v99 offset:60416
	ds_read_b128 v[154:157], v99 offset:64512
	s_waitcnt lgkmcnt(8)
	v_pk_fma_f32 v[160:161], v[8:9], v[110:111], v[160:161]
	v_pk_fma_f32 v[192:193], v[12:13], v[110:111], v[192:193]
	v_pk_fma_f32 v[162:163], v[8:9], v[114:115], v[162:163]
	v_pk_fma_f32 v[194:195], v[12:13], v[114:115], v[194:195]
	v_pk_fma_f32 v[164:165], v[8:9], v[118:119], v[164:165]
	v_pk_fma_f32 v[196:197], v[12:13], v[118:119], v[196:197]
	v_pk_fma_f32 v[166:167], v[8:9], v[122:123], v[166:167]
	v_pk_fma_f32 v[198:199], v[12:13], v[122:123], v[198:199]
	v_pk_fma_f32 v[160:161], v[6:7], v[112:113], v[160:161]
	v_pk_fma_f32 v[192:193], v[10:11], v[112:113], v[192:193]
	v_pk_fma_f32 v[162:163], v[6:7], v[116:117], v[162:163]
	v_pk_fma_f32 v[194:195], v[10:11], v[116:117], v[194:195]
	v_pk_fma_f32 v[164:165], v[6:7], v[120:121], v[164:165]
	v_pk_fma_f32 v[196:197], v[10:11], v[120:121], v[196:197]
	v_pk_fma_f32 v[166:167], v[6:7], v[124:125], v[166:167]
	v_pk_fma_f32 v[198:199], v[10:11], v[124:125], v[198:199]
	ds_read_b128 v[228:231], v100 offset:52224
	ds_read_b128 v[232:235], v100 offset:56320
	ds_read_b128 v[236:239], v100 offset:60416
	ds_read_b128 v[240:243], v100 offset:64512
	s_waitcnt lgkmcnt(8)
; #define LAS __attribute__((address_space(3)))
; __device__ __forceinline__ float dot4(const f32x4 a, const f32x4 b) { return (a[0] * b[0] + a[1] * b[1]) + (a[2] * b[2] + a[3] * b[3]); }
; __device__ __forceinline__ float bfly16(const f32x4 p0, const f32x4 p1, const f32x4 p2, const f32x4 p3, int lane) {
;     const bool b3 = lane & 8, b2 = lane & 4, b1 = lane & 2, b0 = lane & 1;
;     const f32x4 s0 = b3 ? p0 : p2, s1 = b3 ? p1 : p3, k0 = b3 ? p2 : p0, k1 = b3 ? p3 : p1;
;     f32x4 a, c;
;     a[0] = k0[0] + __shfl_xor(s0[0], 8); a[1] = k0[1] + __shfl_xor(s0[1], 8); a[2] = k0[2] + __shfl_xor(s0[2], 8); a[3] = k0[3] + __shfl_xor(s0[3], 8);
;     c[0] = k1[0] + __shfl_xor(s1[0], 8); c[1] = k1[1] + __shfl_xor(s1[1], 8); c[2] = k1[2] + __shfl_xor(s1[2], 8); c[3] = k1[3] + __shfl_xor(s1[3], 8);
;     const f32x4 s4 = b2 ? a : c, k4 = b2 ? c : a;
;     const float d0 = k4[0] + __shfl_xor(s4[0], 4), d1 = k4[1] + __shfl_xor(s4[1], 4), d2 = k4[2] + __shfl_xor(s4[2], 4), d3 = k4[3] + __shfl_xor(s4[3], 4);
;     const float e0 = (b1 ? d2 : d0) + __shfl_xor(b1 ? d0 : d2, 2), e1 = (b1 ? d3 : d1) + __shfl_xor(b1 ? d1 : d3, 2);
; __device__ __forceinline__ void norm_rows2(const f32x4 (&xa)[4], const f32x4 (&xb)[4], const LAS float* gsa, const LAS float* sha, const LAS float* gsb, const LAS float* shb, const LAS float* WgT, ...
;     ...
;     f32x4 pa[4], pb[4];
; #pragma unroll
;     for (int jq = 0; jq < 4; ++jq) { f32x4 sa = (f32x4){0.f, 0.f, 0.f, 0.f}, sb = sa;
; #pragma unroll
;         for (int i = 0; i < 4; ++i) { const LAS float* wp = WgT + (jq * 4) * 1024 + i * 256 + lane * 4;
;             const f32x4 w0 = *(const LAS f32x4*)wp, w1 = *(const LAS f32x4*)(wp + 1024), w2 = *(const LAS f32x4*)(wp + 2048), w3 = *(const LAS f32x4*)(wp + 3072);
;             sa += (f32x4){dot4(ya[i], w0), dot4(ya[i], w1), dot4(ya[i], w2), dot4(ya[i], w3)};
;             sb += (f32x4){dot4(yb[i], w0), dot4(yb[i], w1), dot4(yb[i], w2), dot4(yb[i], w3)}; }
;         pa[jq] = sa; pb[jq] = sb; }
;     const float qa = bfly16(pa[0], pa[1], pa[2], pa[3], lane), qb = bfly16(pb[0], pb[1], pb[2], pb[3], lane);
	v_pk_fma_f32 v[168:169], v[8:9], v[126:127], v[168:169]
	v_pk_fma_f32 v[200:201], v[12:13], v[126:127], v[200:201]
	v_pk_fma_f32 v[170:171], v[8:9], v[130:131], v[170:171]
	v_pk_fma_f32 v[202:203], v[12:13], v[130:131], v[202:203]
	v_pk_fma_f32 v[172:173], v[8:9], v[134:135], v[172:173]
	v_pk_fma_f32 v[204:205], v[12:13], v[134:135], v[204:205]
	v_pk_fma_f32 v[174:175], v[8:9], v[138:139], v[174:175]
	v_pk_fma_f32 v[206:207], v[12:13], v[138:139], v[206:207]
	v_pk_fma_f32 v[168:169], v[6:7], v[128:129], v[168:169]
	v_pk_fma_f32 v[200:201], v[10:11], v[128:129], v[200:201]
	v_pk_fma_f32 v[170:171], v[6:7], v[132:133], v[170:171]
	v_pk_fma_f32 v[202:203], v[10:11], v[132:133], v[202:203]
	v_pk_fma_f32 v[172:173], v[6:7], v[136:137], v[172:173]
	v_pk_fma_f32 v[204:205], v[10:11], v[136:137], v[204:205]
	v_pk_fma_f32 v[174:175], v[6:7], v[140:141], v[174:175]
	v_pk_fma_f32 v[206:207], v[10:11], v[140:141], v[206:207]
	s_waitcnt lgkmcnt(4)
	v_pk_fma_f32 v[176:177], v[8:9], v[142:143], v[176:177]
	v_pk_fma_f32 v[208:209], v[12:13], v[142:143], v[208:209]
	v_pk_fma_f32 v[178:179], v[8:9], v[146:147], v[178:179]
	v_pk_fma_f32 v[210:211], v[12:13], v[146:147], v[210:211]
	v_pk_fma_f32 v[180:181], v[8:9], v[150:151], v[180:181]
	v_pk_fma_f32 v[212:213], v[12:13], v[150:151], v[212:213]
	v_pk_fma_f32 v[182:183], v[8:9], v[154:155], v[182:183]
	v_pk_fma_f32 v[214:215], v[12:13], v[154:155], v[214:215]
	v_pk_fma_f32 v[176:177], v[6:7], v[144:145], v[176:177]
	v_pk_fma_f32 v[208:209], v[10:11], v[144:145], v[208:209]
	v_pk_fma_f32 v[178:179], v[6:7], v[148:149], v[178:179]
	v_pk_fma_f32 v[210:211], v[10:11], v[148:149], v[210:211]
	v_pk_fma_f32 v[180:181], v[6:7], v[152:153], v[180:181]
	v_pk_fma_f32 v[212:213], v[10:11], v[152:153], v[212:213]
	v_pk_fma_f32 v[182:183], v[6:7], v[156:157], v[182:183]
	v_pk_fma_f32 v[214:215], v[10:11], v[156:157], v[214:215]
	s_waitcnt lgkmcnt(0)
	v_pk_fma_f32 v[184:185], v[8:9], v[228:229], v[184:185]
	v_pk_fma_f32 v[216:217], v[12:13], v[228:229], v[216:217]
	v_pk_fma_f32 v[186:187], v[8:9], v[232:233], v[186:187]
	v_pk_fma_f32 v[218:219], v[12:13], v[232:233], v[218:219]
	v_pk_fma_f32 v[188:189], v[8:9], v[236:237], v[188:189]
	v_pk_fma_f32 v[220:221], v[12:13], v[236:237], v[220:221]
	v_pk_fma_f32 v[190:191], v[8:9], v[240:241], v[190:191]
	v_pk_fma_f32 v[222:223], v[12:13], v[240:241], v[222:223]
	v_pk_fma_f32 v[184:185], v[6:7], v[230:231], v[184:185]
	v_pk_fma_f32 v[216:217], v[10:11], v[230:231], v[216:217]
	v_pk_fma_f32 v[186:187], v[6:7], v[234:235], v[186:187]
	v_pk_fma_f32 v[218:219], v[10:11], v[234:235], v[218:219]
	v_pk_fma_f32 v[188:189], v[6:7], v[238:239], v[188:189]
	v_pk_fma_f32 v[220:221], v[10:11], v[238:239], v[220:221]
	v_pk_fma_f32 v[190:191], v[6:7], v[242:243], v[190:191]
	v_pk_fma_f32 v[222:223], v[10:11], v[242:243], v[222:223]
	v_add_f32_e32 v22, v160, v161
	v_add_f32_e32 v23, v162, v163
	v_add_f32_e32 v24, v164, v165
	v_add_f32_e32 v25, v166, v167
	v_add_f32_e32 v78, v168, v169
	v_add_f32_e32 v79, v170, v171
	v_add_f32_e32 v80, v172, v173
	v_add_f32_e32 v81, v174, v175
	v_add_f32_e32 v86, v176, v177
	v_add_f32_e32 v87, v178, v179
	v_add_f32_e32 v88, v180, v181
	v_add_f32_e32 v89, v182, v183
	v_add_f32_e32 v2, v184, v185
	v_add_f32_e32 v3, v186, v187
	v_add_f32_e32 v0, v188, v189
	v_add_f32_e32 v1, v190, v191
	v_add_f32_e32 v26, v192, v193
	v_add_f32_e32 v27, v194, v195
	v_add_f32_e32 v28, v196, v197
	v_add_f32_e32 v29, v198, v199
	v_add_f32_e32 v82, v200, v201
	v_add_f32_e32 v83, v202, v203
	v_add_f32_e32 v84, v204, v205
	v_add_f32_e32 v85, v206, v207
	v_add_f32_e32 v90, v208, v209
	v_add_f32_e32 v91, v210, v211
	v_add_f32_e32 v92, v212, v213
	v_add_f32_e32 v93, v214, v215
	v_add_f32_e32 v12, v216, v217
	v_add_f32_e32 v13, v218, v219
	v_add_f32_e32 v10, v220, v221
	v_add_f32_e32 v11, v222, v223
	v_cndmask_b32_e64 v21, v85, v11, s[6:7]
	v_cndmask_b32_e64 v20, v84, v10, s[6:7]
	v_cndmask_b32_e64 v17, v29, v93, s[6:7]
	v_cndmask_b32_e64 v16, v28, v92, s[6:7]
	v_cndmask_b32_e64 v15, v27, v91, s[6:7]
	v_cndmask_b32_e64 v14, v26, v90, s[6:7]
	v_cndmask_b32_e64 v19, v83, v13, s[6:7]
	v_cndmask_b32_e64 v18, v82, v12, s[6:7]
	ds_bpermute_b32 v14, v95, v14
	ds_bpermute_b32 v15, v95, v15
	ds_bpermute_b32 v16, v95, v16
	ds_bpermute_b32 v17, v95, v17
	ds_bpermute_b32 v18, v95, v18
	ds_bpermute_b32 v19, v95, v19
	ds_bpermute_b32 v20, v95, v20
	ds_bpermute_b32 v21, v95, v21
	v_cndmask_b32_e64 v7, v93, v29, s[6:7]
	v_cndmask_b32_e64 v6, v92, v28, s[6:7]
	v_cndmask_b32_e64 v9, v91, v27, s[6:7]
	v_cndmask_b32_e64 v8, v90, v26, s[6:7]
	v_cndmask_b32_e64 v11, v11, v85, s[6:7]
	v_cndmask_b32_e64 v10, v10, v84, s[6:7]
	v_cndmask_b32_e64 v13, v13, v83, s[6:7]
	v_cndmask_b32_e64 v12, v12, v82, s[6:7]
	s_waitcnt lgkmcnt(6)
	v_pk_add_f32 v[8:9], v[8:9], v[14:15]
	s_waitcnt lgkmcnt(4)
	v_pk_add_f32 v[6:7], v[6:7], v[16:17]
	s_waitcnt lgkmcnt(2)
	v_pk_add_f32 v[12:13], v[12:13], v[18:19]
	s_waitcnt lgkmcnt(0)
	v_pk_add_f32 v[10:11], v[10:11], v[20:21]
	v_cndmask_b32_e64 v18, v8, v12, s[8:9]
	v_cndmask_b32_e64 v15, v7, v11, s[8:9]
	v_cndmask_b32_e64 v17, v6, v10, s[8:9]
	v_cndmask_b32_e64 v16, v9, v13, s[8:9]
	v_cndmask_b32_e64 v14, v11, v7, s[8:9]
	v_cndmask_b32_e64 v6, v10, v6, s[8:9]
	v_cndmask_b32_e64 v10, v13, v9, s[8:9]
	v_cndmask_b32_e64 v8, v12, v8, s[8:9]
	ds_bpermute_b32 v12, v96, v18
	ds_bpermute_b32 v18, v96, v17
	ds_bpermute_b32 v20, v96, v15
	v_cndmask_b32_e64 v7, v25, v89, s[6:7]
	v_cndmask_b32_e64 v9, v24, v88, s[6:7]
	v_cndmask_b32_e64 v11, v23, v87, s[6:7]
	v_cndmask_b32_e64 v13, v22, v86, s[6:7]
	v_cndmask_b32_e64 v15, v81, v1, s[6:7]
	v_cndmask_b32_e64 v17, v80, v0, s[6:7]
	v_cndmask_b32_e64 v19, v79, v3, s[6:7]
	v_cndmask_b32_e64 v21, v78, v2, s[6:7]
	ds_bpermute_b32 v26, v95, v13
	ds_bpermute_b32 v27, v95, v11
	ds_bpermute_b32 v28, v95, v9
	ds_bpermute_b32 v29, v95, v7
	ds_bpermute_b32 v30, v95, v21
	ds_bpermute_b32 v31, v95, v19
	ds_bpermute_b32 v64, v95, v17
	ds_bpermute_b32 v65, v95, v15
	v_cndmask_b32_e64 v25, v89, v25, s[6:7]
	v_cndmask_b32_e64 v24, v88, v24, s[6:7]
	v_cndmask_b32_e64 v23, v87, v23, s[6:7]
	v_cndmask_b32_e64 v22, v86, v22, s[6:7]
	v_cndmask_b32_e64 v1, v1, v81, s[6:7]
	v_cndmask_b32_e64 v0, v0, v80, s[6:7]
	v_cndmask_b32_e64 v3, v3, v79, s[6:7]
	v_cndmask_b32_e64 v2, v2, v78, s[6:7]
	s_waitcnt lgkmcnt(6)
; __device__ __forceinline__ float log_sigmoid(float x) { return fminf(x, 0.f) - log1pf(expf(-fabsf(x))); }
; __device__ __forceinline__ float bfly16(const f32x4 p0, const f32x4 p1, const f32x4 p2, const f32x4 p3, int lane) {
;     ...
;     const f32x4 s4 = b2 ? a : c, k4 = b2 ? c : a;
;     const float d0 = k4[0] + __shfl_xor(s4[0], 4), d1 = k4[1] + __shfl_xor(s4[1], 4), d2 = k4[2] + __shfl_xor(s4[2], 4), d3 = k4[3] + __shfl_xor(s4[3], 4);
;     const float e0 = (b1 ? d2 : d0) + __shfl_xor(b1 ? d0 : d2, 2), e1 = (b1 ? d3 : d1) + __shfl_xor(b1 ? d1 : d3, 2);
;     float q1 = (b0 ? e1 : e0) + __shfl_xor(b0 ? e0 : e1, 1);
;     q1 += __shfl_xor(q1, 16); q1 += __shfl_xor(q1, 32);
;     return q1;
; __device__ __forceinline__ void norm_rows2(const f32x4 (&xa)[4], const f32x4 (&xb)[4], const LAS float* gsa, const LAS float* sha, const LAS float* gsb, const LAS float* shb, const LAS float* WgT, ...
;     ...
;     if (lane < 16) { const float gbv = gate_b[lane]; const bool ls = (lane >> 2) & 1;
;         const float prea = qa + gbv, preb = qb + gbv;
;         ga[0] = ls ? log_sigmoid(prea) : prea; gb[0] = ls ? log_sigmoid(preb) : preb; }
	v_pk_add_f32 v[22:23], v[22:23], v[26:27]
	s_waitcnt lgkmcnt(4)
	v_pk_add_f32 v[24:25], v[24:25], v[28:29]
	s_waitcnt lgkmcnt(2)
	v_pk_add_f32 v[2:3], v[2:3], v[30:31]
	s_waitcnt lgkmcnt(0)
	v_pk_add_f32 v[0:1], v[0:1], v[64:65]
	v_cndmask_b32_e64 v17, v23, v3, s[8:9]
	v_cndmask_b32_e64 v21, v25, v1, s[8:9]
	v_cndmask_b32_e64 v13, v22, v2, s[8:9]
	ds_bpermute_b32 v16, v96, v16
	v_cndmask_b32_e64 v9, v24, v0, s[8:9]
	ds_bpermute_b32 v13, v96, v13
	ds_bpermute_b32 v17, v96, v17
	ds_bpermute_b32 v21, v96, v21
	ds_bpermute_b32 v19, v96, v9
	v_cndmask_b32_e64 v15, v1, v25, s[8:9]
	v_cndmask_b32_e64 v11, v3, v23, s[8:9]
	v_cndmask_b32_e64 v9, v2, v22, s[8:9]
	v_cndmask_b32_e64 v7, v0, v24, s[8:9]
	s_waitcnt lgkmcnt(3)
	v_pk_add_f32 v[0:1], v[8:9], v[12:13]
	s_waitcnt lgkmcnt(2)
	v_pk_add_f32 v[8:9], v[10:11], v[16:17]
	s_waitcnt lgkmcnt(1)
	v_pk_add_f32 v[10:11], v[14:15], v[20:21]
	s_waitcnt lgkmcnt(0)
	v_pk_add_f32 v[2:3], v[6:7], v[18:19]
	v_cndmask_b32_e64 v7, v8, v10, s[12:13]
	v_cndmask_b32_e64 v6, v0, v2, s[12:13]
	ds_bpermute_b32 v12, v97, v7
	v_cndmask_b32_e64 v7, v1, v3, s[12:13]
	v_cndmask_b32_e64 v1, v3, v1, s[12:13]
	v_cndmask_b32_e64 v3, v9, v11, s[12:13]
	ds_bpermute_b32 v6, v97, v6
	ds_bpermute_b32 v7, v97, v7
	ds_bpermute_b32 v13, v97, v3
	v_cndmask_b32_e64 v0, v2, v0, s[12:13]
	v_cndmask_b32_e64 v3, v11, v9, s[12:13]
	v_cndmask_b32_e64 v2, v10, v8, s[12:13]
	s_waitcnt lgkmcnt(1)
	v_pk_add_f32 v[0:1], v[0:1], v[6:7]
	s_waitcnt lgkmcnt(0)
	v_pk_add_f32 v[2:3], v[2:3], v[12:13]
	s_nop 0
	v_cndmask_b32_e64 v6, v0, v2, s[14:15]
	v_cndmask_b32_e64 v7, v1, v3, s[14:15]
	ds_bpermute_b32 v6, v98, v6
	ds_bpermute_b32 v7, v98, v7
	v_cndmask_b32_e64 v1, v3, v1, s[14:15]
	v_cndmask_b32_e64 v0, v2, v0, s[14:15]
	s_waitcnt lgkmcnt(0)
	v_pk_add_f32 v[0:1], v[0:1], v[6:7]
	ds_bpermute_b32 v2, v94, v0
	ds_bpermute_b32 v3, v94, v1
	s_waitcnt lgkmcnt(0)
	v_pk_add_f32 v[0:1], v[0:1], v[2:3]
	ds_bpermute_b32 v2, v53, v0
	ds_bpermute_b32 v3, v53, v1
	s_and_saveexec_b64 s[30:31], s[16:17]
	s_cbranch_execz .LBB0_109
	global_load_dword v4, v[44:45], off
	s_waitcnt lgkmcnt(0)
	v_pk_add_f32 v[0:1], v[0:1], v[2:3]
	s_waitcnt vmcnt(0)
	v_pk_add_f32 v[0:1], v[0:1], v[4:5] op_sel_hi:[1,0]
	s_and_saveexec_b64 s[80:81], s[10:11]
	s_cbranch_execz .LBB0_108
	v_mul_f32_e64 v2, |v0|, s35
	v_rndne_f32_e32 v3, v2
	v_sub_f32_e32 v4, v2, v3
	v_fma_f32 v2, |v0|, s35, -v2
	v_fma_f32 v2, |v0|, s47, v2
	v_add_f32_e32 v2, v4, v2
	v_exp_f32_e32 v4, v2
	v_cvt_i32_f32_e32 v3, v3
	v_cmp_ngt_f32_e64 s[28:29], |v0|, s53
	v_max_f32_e32 v2, v0, v0
	v_min_f32_e32 v2, 0, v2
	v_ldexp_f32 v3, v4, v3
	v_cndmask_b32_e64 v3, 0, v3, s[28:29]
	v_cmp_nlt_f32_e64 s[28:29], |v0|, s75
	s_nop 1
	v_cndmask_b32_e64 v30, v107, v3, s[28:29]
	v_add_f32_e32 v6, 1.0, v30
	v_add_f32_e32 v0, -1.0, v6
	v_sub_f32_e32 v3, v0, v6
	v_add_f32_e32 v3, 1.0, v3
	v_sub_f32_e32 v0, v30, v0
	v_add_f32_e32 v7, v0, v3
	v_mul_f32_e64 v0, |v1|, s35
	v_rndne_f32_e32 v3, v0
	v_sub_f32_e32 v9, v0, v3
	v_fma_f32 v0, |v1|, s35, -v0
	v_fma_f32 v0, |v1|, s47, v0
	v_add_f32_e32 v0, v9, v0
	v_exp_f32_e32 v0, v0
	v_cvt_i32_f32_e32 v9, v3
	v_cmp_ngt_f32_e64 s[28:29], |v1|, s53
	v_cvt_f64_f32_e32 v[4:5], v6
	v_frexp_exp_i32_f64_e32 v4, v[4:5]
	v_ldexp_f32 v0, v0, v9
	v_cndmask_b32_e64 v0, 0, v0, s[28:29]
	v_cmp_nlt_f32_e64 s[28:29], |v1|, s75
	v_max_f32_e32 v3, v1, v1
	v_frexp_mant_f32_e32 v8, v6
	v_cndmask_b32_e64 v31, v107, v0, s[28:29]
	v_add_f32_e32 v5, 1.0, v31
	v_add_f32_e32 v0, -1.0, v5
	v_sub_f32_e32 v1, v0, v5
	v_add_f32_e32 v1, 1.0, v1
	v_sub_f32_e32 v0, v31, v0
	v_add_f32_e32 v9, v0, v1
	v_frexp_mant_f32_e32 v10, v5
	v_cvt_f64_f32_e32 v[0:1], v5
	v_frexp_exp_i32_f64_e32 v0, v[0:1]
	v_cmp_gt_f32_e64 s[28:29], s79, v10
	v_min_f32_e32 v3, 0, v3
	s_nop 0
	v_subbrev_co_u32_e64 v22, s[28:29], 0, v0, s[28:29]
	v_cmp_gt_f32_e64 s[28:29], s79, v8
	s_nop 1
	v_subbrev_co_u32_e64 v23, s[28:29], 0, v4, s[28:29]
	v_sub_u32_e32 v1, 0, v23
	v_ldexp_f32 v0, v6, v1
	v_sub_u32_e32 v6, 0, v22
	v_ldexp_f32 v4, v7, v1
	v_ldexp_f32 v1, v5, v6
	v_ldexp_f32 v5, v9, v6
	v_pk_add_f32 v[6:7], v[0:1], 1.0 op_sel_hi:[1,0]
	v_pk_add_f32 v[14:15], v[0:1], -1.0 op_sel_hi:[1,0]
	v_pk_add_f32 v[8:9], v[6:7], -1.0 op_sel_hi:[1,0]
	v_pk_add_f32 v[16:17], v[14:15], 1.0 op_sel_hi:[1,0]
	v_pk_add_f32 v[8:9], v[0:1], v[8:9] neg_lo:[0,1] neg_hi:[0,1]
	v_pk_add_f32 v[0:1], v[0:1], v[16:17] neg_lo:[0,1] neg_hi:[0,1]
	v_pk_add_f32 v[8:9], v[4:5], v[8:9]
	v_pk_add_f32 v[0:1], v[4:5], v[0:1]
	v_pk_add_f32 v[10:11], v[6:7], v[8:9]
	v_pk_add_f32 v[4:5], v[14:15], v[0:1]
	v_rcp_f32_e32 v12, v10
	v_rcp_f32_e32 v13, v11
	v_pk_add_f32 v[6:7], v[6:7], v[10:11] neg_lo:[0,1] neg_hi:[0,1]
	v_pk_add_f32 v[14:15], v[14:15], v[4:5] neg_lo:[0,1] neg_hi:[0,1]
	v_pk_add_f32 v[6:7], v[8:9], v[6:7]
	v_pk_mul_f32 v[8:9], v[4:5], v[12:13]
	v_pk_add_f32 v[0:1], v[0:1], v[14:15]
	v_pk_mul_f32 v[14:15], v[10:11], v[8:9]
	v_cmp_neq_f32_e64 s[28:29], s77, v30
	v_pk_fma_f32 v[16:17], v[8:9], v[10:11], v[14:15] neg_lo:[0,0,1] neg_hi:[0,0,1]
	s_nop 0
	v_pk_fma_f32 v[16:17], v[8:9], v[6:7], v[16:17]
	s_nop 0
	v_pk_add_f32 v[18:19], v[14:15], v[16:17]
	s_nop 0
	v_pk_add_f32 v[20:21], v[4:5], v[18:19] neg_lo:[0,1] neg_hi:[0,1]
	v_pk_add_f32 v[14:15], v[18:19], v[14:15] neg_lo:[0,1] neg_hi:[0,1]
	v_pk_add_f32 v[4:5], v[4:5], v[20:21] neg_lo:[0,1] neg_hi:[0,1]
; __device__ __forceinline__ float log_sigmoid(float x) { return fminf(x, 0.f) - log1pf(expf(-fabsf(x))); }
; __device__ __forceinline__ void norm_rows2(const f32x4 (&xa)[4], const f32x4 (&xb)[4], const LAS float* gsa, const LAS float* sha, const LAS float* gsb, const LAS float* shb, const LAS float* WgT, ...
;     ...
;     if (lane < 16) { const float gbv = gate_b[lane]; const bool ls = (lane >> 2) & 1;
;         const float prea = qa + gbv, preb = qb + gbv;
;         ga[0] = ls ? log_sigmoid(prea) : prea; gb[0] = ls ? log_sigmoid(preb) : preb; }
	s_nop 0
	v_pk_add_f32 v[4:5], v[4:5], v[18:19] neg_lo:[0,1] neg_hi:[0,1]
	s_nop 0
	v_pk_add_f32 v[0:1], v[0:1], v[4:5]
	v_pk_add_f32 v[4:5], v[14:15], v[16:17] neg_lo:[0,1] neg_hi:[0,1]
	s_nop 0
	v_pk_add_f32 v[0:1], v[4:5], v[0:1]
	s_nop 0
	v_pk_add_f32 v[4:5], v[20:21], v[0:1]
	s_nop 0
	v_pk_mul_f32 v[14:15], v[12:13], v[4:5]
	s_nop 0
	v_pk_mul_f32 v[16:17], v[10:11], v[14:15]
	s_nop 0
	v_pk_fma_f32 v[10:11], v[14:15], v[10:11], v[16:17] neg_lo:[0,0,1] neg_hi:[0,0,1]
	s_nop 0
	v_pk_fma_f32 v[6:7], v[14:15], v[6:7], v[10:11]
	v_pk_add_f32 v[10:11], v[20:21], v[4:5] neg_lo:[0,1] neg_hi:[0,1]
	s_nop 0
	v_pk_add_f32 v[0:1], v[0:1], v[10:11]
	v_pk_add_f32 v[10:11], v[16:17], v[6:7]
	s_nop 0
	v_pk_add_f32 v[18:19], v[4:5], v[10:11] neg_lo:[0,1] neg_hi:[0,1]
	v_pk_add_f32 v[16:17], v[10:11], v[16:17] neg_lo:[0,1] neg_hi:[0,1]
	v_pk_add_f32 v[4:5], v[4:5], v[18:19] neg_lo:[0,1] neg_hi:[0,1]
	s_nop 0
	v_pk_add_f32 v[4:5], v[4:5], v[10:11] neg_lo:[0,1] neg_hi:[0,1]
	s_nop 0
	v_pk_add_f32 v[0:1], v[0:1], v[4:5]
	v_pk_add_f32 v[4:5], v[16:17], v[6:7] neg_lo:[0,1] neg_hi:[0,1]
	s_nop 0
	v_pk_add_f32 v[0:1], v[4:5], v[0:1]
	v_pk_add_f32 v[4:5], v[8:9], v[14:15]
	v_pk_add_f32 v[0:1], v[18:19], v[0:1]
	v_pk_add_f32 v[6:7], v[4:5], v[8:9] neg_lo:[0,1] neg_hi:[0,1]
	v_pk_mul_f32 v[0:1], v[12:13], v[0:1]
	v_pk_add_f32 v[6:7], v[14:15], v[6:7] neg_lo:[0,1] neg_hi:[0,1]
	v_cvt_f32_i32_e32 v9, v22
	v_pk_add_f32 v[0:1], v[6:7], v[0:1]
	v_cvt_f32_i32_e32 v8, v23
	v_pk_add_f32 v[6:7], v[4:5], v[0:1]
	v_pk_mul_f32 v[14:15], v[8:9], s[76:77] op_sel_hi:[1,0]
	v_pk_mul_f32 v[10:11], v[6:7], v[6:7]
	v_pk_add_f32 v[4:5], v[6:7], v[4:5] neg_lo:[0,1] neg_hi:[0,1]
	v_pk_fma_f32 v[12:13], v[10:11], s[52:53], v[52:53] op_sel_hi:[1,0,0]
	v_pk_add_f32 v[0:1], v[0:1], v[4:5] neg_lo:[0,1] neg_hi:[0,1]
	v_ldexp_f32 v4, v6, 1
	v_pk_fma_f32 v[12:13], v[10:11], v[12:13], s[74:75] op_sel_hi:[1,1,0]
	v_ldexp_f32 v5, v7, 1
	v_pk_mul_f32 v[6:7], v[6:7], v[10:11]
	v_pk_fma_f32 v[16:17], v[8:9], s[76:77], v[14:15] op_sel_hi:[1,0,1] neg_lo:[0,0,1] neg_hi:[0,0,1]
	v_pk_mul_f32 v[6:7], v[6:7], v[12:13]
	v_mov_b32_e32 v19, v5
	v_pk_add_f32 v[10:11], v[4:5], v[6:7]
	v_ldexp_f32 v0, v0, 1
	v_pk_add_f32 v[4:5], v[10:11], v[4:5] neg_lo:[0,1] neg_hi:[0,1]
	v_pk_fma_f32 v[8:9], v[8:9], s[78:79], v[16:17] op_sel_hi:[1,0,1]
	v_ldexp_f32 v1, v1, 1
	v_pk_add_f32 v[4:5], v[6:7], v[4:5] neg_lo:[0,1] neg_hi:[0,1]
	v_mov_b32_e32 v12, v14
	v_mov_b32_e32 v13, v7
	v_mov_b32_e32 v18, v8
	v_pk_add_f32 v[6:7], v[0:1], v[4:5]
	v_mov_b32_e32 v4, v14
	v_mov_b32_e32 v0, v8
	v_pk_add_f32 v[12:13], v[12:13], v[18:19]
	v_pk_add_f32 v[18:19], v[4:5], v[0:1]
	v_mov_b32_e32 v0, v10
	v_mov_b32_e32 v4, v6
	v_pk_add_f32 v[16:17], v[14:15], v[8:9]
	v_pk_add_f32 v[0:1], v[0:1], v[4:5]
	v_pk_add_f32 v[4:5], v[10:11], v[6:7]
	v_mov_b32_e32 v20, v16
	v_mov_b32_e32 v21, v15
	v_mov_b32_e32 v22, v4
	v_mov_b32_e32 v23, v9
	v_pk_add_f32 v[0:1], v[12:13], v[0:1]
	v_pk_add_f32 v[12:13], v[16:17], v[4:5]
	v_pk_add_f32 v[24:25], v[20:21], v[22:23]
	v_mov_b32_e32 v26, v4
	v_mov_b32_e32 v27, v13
	v_mov_b32_e32 v28, v10
	v_mov_b32_e32 v29, v17
	v_pk_add_f32 v[20:21], v[24:25], v[20:21] neg_lo:[0,1] neg_hi:[0,1]
	v_pk_add_f32 v[26:27], v[26:27], v[28:29] neg_lo:[0,1] neg_hi:[0,1]
	v_pk_add_f32 v[24:25], v[16:17], v[14:15] neg_lo:[0,1] neg_hi:[0,1]
	v_pk_add_f32 v[22:23], v[22:23], v[20:21] neg_lo:[0,1] neg_hi:[0,1]
	v_mov_b32_e32 v28, v16
	v_mov_b32_e32 v29, v13
	v_mov_b32_e32 v15, v27
	v_mov_b32_e32 v21, v11
	v_pk_add_f32 v[10:11], v[4:5], v[10:11] neg_lo:[0,1] neg_hi:[0,1]
	v_pk_add_f32 v[14:15], v[28:29], v[14:15] neg_lo:[0,1] neg_hi:[0,1]
	v_pk_add_f32 v[24:25], v[8:9], v[24:25] neg_lo:[0,1] neg_hi:[0,1]
	v_pk_add_f32 v[0:1], v[0:1], v[20:21] neg_lo:[0,1] neg_hi:[0,1]
	v_pk_add_f32 v[10:11], v[6:7], v[10:11] neg_lo:[0,1] neg_hi:[0,1]
	v_mov_b32_e32 v9, v17
	v_mov_b32_e32 v7, v5
	v_pk_add_f32 v[0:1], v[18:19], v[0:1] neg_lo:[0,1] neg_hi:[0,1]
	v_pk_add_f32 v[8:9], v[8:9], v[14:15] neg_lo:[0,1] neg_hi:[0,1]
	v_pk_add_f32 v[4:5], v[6:7], v[26:27] neg_lo:[0,1] neg_hi:[0,1]
	v_pk_add_f32 v[14:15], v[22:23], v[0:1]
	v_pk_add_f32 v[6:7], v[4:5], v[8:9]
	v_mov_b32_e32 v5, v1
	v_pk_add_f32 v[0:1], v[24:25], v[4:5]
	v_mov_b32_e32 v9, v23
	v_pk_add_f32 v[0:1], v[0:1], v[8:9] neg_lo:[0,1] neg_hi:[0,1]
	v_mov_b32_e32 v4, v6
	v_mov_b32_e32 v5, v15
	v_pk_add_f32 v[4:5], v[4:5], v[0:1] neg_lo:[0,1] neg_hi:[0,1]
	v_pk_add_f32 v[0:1], v[10:11], v[0:1] neg_lo:[0,1] neg_hi:[0,1]
	v_pk_add_f32 v[4:5], v[8:9], v[4:5] neg_lo:[0,1] neg_hi:[0,1]
	s_nop 0
	v_pk_add_f32 v[0:1], v[0:1], v[4:5]
	v_pk_add_f32 v[4:5], v[14:15], v[6:7]
	s_nop 0
	v_pk_add_f32 v[6:7], v[12:13], v[4:5]
	s_nop 0
	v_pk_add_f32 v[8:9], v[6:7], v[12:13] neg_lo:[0,1] neg_hi:[0,1]
	s_nop 0
	v_pk_add_f32 v[4:5], v[4:5], v[8:9] neg_lo:[0,1] neg_hi:[0,1]
	s_nop 0
	v_pk_add_f32 v[0:1], v[0:1], v[4:5]
	s_nop 0
	v_pk_add_f32 v[0:1], v[6:7], v[0:1]
	s_nop 0
	v_cndmask_b32_e64 v0, v107, v0, s[28:29]
	v_cmp_neq_f32_e64 s[28:29], s77, v31
	s_nop 1
	v_cndmask_b32_e64 v1, v107, v1, s[28:29]
	v_cmp_lt_f32_e64 s[28:29], |v31|, s92
	s_nop 1
	v_cndmask_b32_e64 v1, v1, v31, s[28:29]
	v_cmp_lt_f32_e64 s[28:29], |v30|, s92
	s_nop 1
	v_cndmask_b32_e64 v0, v0, v30, s[28:29]
	v_pk_add_f32 v[0:1], v[2:3], v[0:1] neg_lo:[0,1] neg_hi:[0,1]
	s_branch .LBB0_108
